# attention loop: DMA pointers on SALU with SGPR base, V fragments loaded in order of need (uniform 4-slot prefetch), DMA issue moved into MFMA slots 5 and 9
# speedup vs baseline: 1.0533x; 1.0044x over previous
; #define LAS __attribute__((address_space(3)))
; __device__ __forceinline__ int v_rd_base(int lane) { return (((lane & 3) << 3) | (((lane >> 2) & 3) << 6) | (((lane >> 4) & 1) << 5)) + ((lane >> 5) & 1) * 1024; }
; #define DMA(t) do { const int t_ = (t) < NT ? (t) : NT - 1; const long off_ = (long)t_ * (KVBLK * LDK); \
;         __builtin_amdgcn_global_load_lds((const unsigned*)(kptr + off_), (LAS unsigned*)(ldsK + SLOT(t)), 16, 0, 0); \
;         __builtin_amdgcn_global_load_lds((const unsigned*)(vptr + off_), (LAS unsigned*)(ldsV + SLOT(t)), 16, 0, 0); } while (0)
; #define WBAR(N) asm volatile("s_waitcnt vmcnt(" #N ") lgkmcnt(0)\n\ts_barrier" ::: "memory")
; __device__ __forceinline__ void attn_body(const bf16* __restrict__ Qb, const bf16* __restrict__ Kh, const bf16* __restrict__ Vh, bf16* __restrict__ Ob, int seq, float m0l2, char* lds, bool pre, bool post) {
;     ...
;     const int wsg = __builtin_amdgcn_readfirstlane(wid);
;     const int oo = (wsg * 64 + lane) * 16;
;     const int ksr = oo >> 8, kcolB = (oo & 255) ^ ((ksr & 15) << 4);
;     const bf16* kptr = Kh + (long)(ksr + 32 * (kcolB >> 7)) * LDK + ((kcolB & 127) >> 1);
;     const int vkk = ((oo >> 9) >> 1) * 8 + ((oo & 511) >> 6), vcc = ((oo >> 9) & 1) * 32 + ((oo & 63) >> 1);
;     const bf16* vptr = Vh + (long)((vkk & ~0xC) | ((vkk & 4) << 1) | ((vkk & 8) >> 1)) * LDK + vcc;
;     LAS unsigned char* const ldsK = (LAS unsigned char*)lds + OFF_K + wsg * 1024; LAS unsigned char* const ldsV = (LAS unsigned char*)lds + OFF_V + wsg * 1024;
;     const int vb0 = (int)(uintptr_t)V_lds + v_rd_base(lane);
;     const int NT = seq / KVBLK;
;     ...
;     f32x16 pA0, pA1, pB0, pB1; bf16x8 pa0, pa1, pa2, pa3;
;     ...
;     if (!pre) { DMA(0); DMA(1); } DMA(2); WBAR(2);
;     qkt(pA0, pA1, K_lds, qr, negm, r32, hi); partialSM(pA0);
.LBB0_26:
	s_lshl_b32 s25, s7, 6
	s_cmp_lg_u32 0, -1
	s_cselect_b32 s39, 0, 0
	v_lshl_add_u64 v[16:17], v[132:133], 0, s[82:83]
	s_add_i32 m0, s26, 0xc000
	v_lshlrev_b32_e32 v39, 8, v150
	global_load_lds_dwordx4 v[16:17], off
	v_lshl_add_u64 v[16:17], v[134:135], 0, s[82:83]
	s_add_i32 m0, s26, 0x4000
	s_movk_i32 s7, 0xc0
	global_load_lds_dwordx4 v[16:17], off
	v_lshlrev_b32_e32 v16, 4, v150
	v_and_b32_e32 v80, 0xf0, v16
	v_lshrrev_b32_e32 v39, 4, v150
	v_lshlrev_b32_e32 v39, 11, v39
	v_lshl_add_u32 v39, v130, 4, v39
	v_add_u32_e32 v39, v39, v80
	v_mov_b32_e32 v163, v39
	s_waitcnt vmcnt(2) lgkmcnt(0)
	s_barrier
	v_add_u32_e32 v154, 0, v163
	ds_read_b128 v[40:43], v154 offset:32768
	v_or_b32_e32 v16, 0x80, v130
	v_add_u32_e32 v164, 4096, v39
	v_add_u32_e32 v162, 0, v164
	ds_read_b128 v[44:47], v162 offset:32768
	s_waitcnt vmcnt(0) lgkmcnt(0)
	v_mfma_f32_32x32x16_bf16 v[16:31], v[40:43], v[124:127], v[48:63]
	v_or_b32_e32 v40, 32, v130
	v_add_u32_e32 v165, 512, v39
	v_add_u32_e32 v153, 0, v165
	ds_read_b128 v[40:43], v153 offset:32768
	s_add_i32 s38, s38, s37
	v_mfma_f32_32x32x16_bf16 v[64:79], v[44:47], v[124:127], v[48:63]
	v_or_b32_e32 v44, 0xa0, v130
	v_add_u32_e32 v166, 4608, v39
	v_add_u32_e32 v157, 0, v166
	ds_read_b128 v[44:47], v157 offset:32768
	s_waitcnt lgkmcnt(1)
	v_mfma_f32_32x32x16_bf16 v[16:31], v[40:43], v[120:123], v[16:31]
	v_or_b32_e32 v40, 64, v130
	v_add_u32_e32 v167, 1024, v39
	v_add_u32_e32 v156, 0, v167
	ds_read_b128 v[40:43], v156 offset:32768
	s_waitcnt lgkmcnt(1)
	v_mfma_f32_32x32x16_bf16 v[64:79], v[44:47], v[120:123], v[64:79]
	v_or_b32_e32 v44, 0xc0, v130
	v_add_u32_e32 v168, 5120, v39
	v_add_u32_e32 v158, 0, v168
	ds_read_b128 v[44:47], v158 offset:32768
	s_waitcnt lgkmcnt(1)
	v_mfma_f32_32x32x16_bf16 v[16:31], v[40:43], v[116:119], v[16:31]
	v_or_b32_e32 v40, 0x60, v130
	v_add_u32_e32 v169, 1536, v39
	v_add_u32_e32 v155, 0, v169
	ds_read_b128 v[40:43], v155 offset:32768
	s_waitcnt lgkmcnt(1)
	v_mfma_f32_32x32x16_bf16 v[64:79], v[44:47], v[116:119], v[64:79]
	v_or_b32_e32 v44, 0xe0, v130
	v_add_u32_e32 v170, 5632, v39
	v_add_u32_e32 v159, 0, v170
	ds_read_b128 v[44:47], v159 offset:32768
	v_lshlrev_b32_e32 v39, 1, v131
	v_and_b32_e32 v39, 32, v39
	v_and_or_b32 v38, v38, s7, v39
	s_waitcnt lgkmcnt(1)
	v_mfma_f32_32x32x16_bf16 v[16:31], v[40:43], v[112:115], v[16:31]
	v_lshlrev_b32_e32 v39, 5, v131
	v_and_b32_e32 v39, 0x400, v39
	v_or3_b32 v129, v38, v39, v35
	v_add_u32_e32 v172, s39, v129
	s_mov_b32 s7, -1
	s_nop 6
	v_exp_f32_e32 v183, v16
	s_waitcnt lgkmcnt(0)
	v_mfma_f32_32x32x16_bf16 v[64:79], v[44:47], v[112:115], v[64:79]
	v_exp_f32_e32 v188, v17
	v_mad_u64_u32 v[16:17], s[46:47], s27, v211, v[32:33]
	v_lshl_add_u64 v[16:17], v[16:17], 0, v[160:161]
	v_lshl_add_u64 v[140:141], s[28:29], 0, v[16:17]
	v_add3_u32 v16, s38, v37, v36
	v_ashrrev_i32_e32 v17, 31, v16
	v_exp_f32_e32 v185, v18
	v_exp_f32_e32 v187, v19
	v_exp_f32_e32 v184, v20
	v_exp_f32_e32 v186, v21
	v_exp_f32_e32 v181, v22
	v_exp_f32_e32 v182, v23
	v_exp_f32_e32 v178, v24
	v_exp_f32_e32 v180, v25
	v_exp_f32_e32 v176, v26
	v_exp_f32_e32 v179, v27
	v_exp_f32_e32 v175, v28
	v_exp_f32_e32 v177, v29
	v_exp_f32_e32 v173, v30
	v_exp_f32_e32 v174, v31
	v_lshlrev_b64 v[16:17], 8, v[16:17]
	v_mad_u64_u32 v[16:17], s[38:39], s27, v211, v[16:17]
	v_add_u32_e32 v18, v34, v35
	v_lshl_or_b32 v16, v18, 1, v16
	v_mov_b32_e32 v160, 0
	v_lshl_add_u64 v[142:143], s[28:29], 0, v[16:17]
	s_mov_b32 s27, 0x8000
	v_mov_b32_e32 v16, 0
	v_mov_b32_e32 v17, v160
	v_mov_b32_e32 v18, v160
	v_mov_b32_e32 v19, v160
	v_mov_b32_e32 v20, v160
	v_mov_b32_e32 v21, v160
	v_mov_b32_e32 v22, v160
	v_mov_b32_e32 v23, v160
	v_mov_b32_e32 v24, v160
	v_mov_b32_e32 v25, v160
	v_mov_b32_e32 v26, v160
	v_mov_b32_e32 v27, v160
	v_mov_b32_e32 v28, v160
	v_mov_b32_e32 v29, v160
	v_mov_b32_e32 v30, v160
	v_mov_b32_e32 v31, v160
	v_mov_b32_e32 v32, 0
	v_mov_b32_e32 v33, v160
	v_mov_b32_e32 v34, v160
	v_mov_b32_e32 v35, v160
	v_mov_b32_e32 v36, v160
	v_mov_b32_e32 v37, v160
	v_mov_b32_e32 v38, v160
	v_mov_b32_e32 v39, v160
	v_mov_b32_e32 v40, v160
	v_mov_b32_e32 v41, v160
	v_mov_b32_e32 v42, v160
	v_mov_b32_e32 v43, v160
	v_mov_b32_e32 v44, v160
	v_mov_b32_e32 v45, v160
	v_mov_b32_e32 v46, v160
	v_mov_b32_e32 v47, v160
	v_lshl_add_u64 v[140:141], v[140:141], 0, s[72:73]
	v_lshl_add_u64 v[142:143], v[142:143], 0, s[72:73]
	s_mov_b64 s[38:39], 0x10e06000
	s_mov_b64 s[46:47], 0x11686000
	v_lshl_add_u64 v[140:141], v[140:141], 0, s[38:39]
	v_lshl_add_u64 v[142:143], v[142:143], 0, s[46:47]
	s_nop 0
	v_readfirstlane_b32 s50, v140
	v_readfirstlane_b32 s51, v141
	v_readfirstlane_b32 s52, v142
	v_readfirstlane_b32 s53, v143
	s_sub_u32 s50, s50, 0x10000
	s_subb_u32 s51, s51, 0
	s_sub_u32 s52, s52, 0x10000
	s_subb_u32 s53, s53, 0
	v_subrev_u32_e32 v140, s50, v140
	v_subrev_u32_e32 v142, s52, v142
	ds_read_b128 v[234:237], v163 offset:40960
	ds_read_b128 v[238:241], v165 offset:40960
	ds_read_b128 v[242:245], v167 offset:40960
	ds_read_b128 v[246:249], v169 offset:40960
	v_readfirstlane_b32 s37, v151
	s_nop 0
	s_cmp_ge_u32 s37, 4
	s_cbranch_scc0 .Lattn_prio_skip
	s_setprio 1
; #define LAS __attribute__((address_space(3)))
; __device__ __forceinline__ void qkt(f32x16& p0, f32x16& p1, const char* Ks, const bf16x8* qr, const f32x16& negm, int r32, int hi) {
; #pragma unroll
;     for (int d0 = 0; d0 < 4; ++d0) { const int cb = (d0 * 16 + hi * 8) * 2;
;         const bf16x8 b0 = *reinterpret_cast<const bf16x8*>(Ks + KSWZ(r32, cb));
;         const bf16x8 b1 = *reinterpret_cast<const bf16x8*>(Ks + KSWZ(r32, 128 + cb));
;         if (d0 == 0) { p0 = __builtin_amdgcn_mfma_f32_32x32x16_bf16(b0, qr[0], negm, 0, 0, 0); p1 = __builtin_amdgcn_mfma_f32_32x32x16_bf16(b1, qr[0], negm, 0, 0, 0); }
;         else { p0 = __builtin_amdgcn_mfma_f32_32x32x16_bf16(b0, qr[d0], p0, 0, 0, 0); p1 = __builtin_amdgcn_mfma_f32_32x32x16_bf16(b1, qr[d0], p1, 0, 0, 0); } }
; }
; __device__ __forceinline__ int v_st(int k, int c) { const int kk = (k & ~0xC) | ((k & 4) << 1) | ((k & 8) >> 1); return ((kk >> 3) * 2 + (c >> 5)) * 512 + ((kk & 7) * 32 + (c & 31)) * 2; }
; __device__ __forceinline__ int v_rd_base(int lane) { return (((lane & 3) << 3) | (((lane >> 2) & 3) << 6) | (((lane >> 4) & 1) << 5)) + ((lane >> 5) & 1) * 1024; }
; template <int OFF> __device__ __forceinline__ s16x4 tr_read(int vb) {
;     return __builtin_bit_cast(s16x4, __builtin_amdgcn_ds_read_tr16_b64_v4i16((LAS v4i16_t*)(unsigned)(vb + OFF)));
; }
; template <int D0> __device__ __forceinline__ void pv_one(f32x16& od, int vb, bf16x8 pa0, bf16x8 pa1, bf16x8 pa2, bf16x8 pa3) {
;     const s16x4 l0 = tr_read<v_rd_off(D0, 0, 0)>(vb), h0 = tr_read<v_rd_off(D0, 0, 1)>(vb), l1 = tr_read<v_rd_off(D0, 1, 0)>(vb), h1 = tr_read<v_rd_off(D0, 1, 1)>(vb);
;     const s16x4 l2 = tr_read<v_rd_off(D0, 2, 0)>(vb), h2 = tr_read<v_rd_off(D0, 2, 1)>(vb), l3 = tr_read<v_rd_off(D0, 3, 0)>(vb), h3 = tr_read<v_rd_off(D0, 3, 1)>(vb);
;     ...
;     od = __builtin_amdgcn_mfma_f32_32x32x16_bf16(pa0, PK(l0, h0), od, 0, 0, 0);
;     od = __builtin_amdgcn_mfma_f32_32x32x16_bf16(pa1, PK(l1, h1), od, 0, 0, 0);
;     od = __builtin_amdgcn_mfma_f32_32x32x16_bf16(pa2, PK(l2, h2), od, 0, 0, 0);
;     od = __builtin_amdgcn_mfma_f32_32x32x16_bf16(pa3, PK(l3, h3), od, 0, 0, 0);
;     ...
; }
; __device__ __forceinline__ void pv_d0(f32x16* o, int vb, bf16x8 pa0, bf16x8 pa1, bf16x8 pa2, bf16x8 pa3) {
;     pv_one<0>(o[0], vb, pa0, pa1, pa2, pa3); pv_one<1>(o[1], vb, pa0, pa1, pa2, pa3);
; }
.Lattn_prio_skip:
.LBB0_27:
	s_waitcnt lgkmcnt(3)
	v_mfma_f32_32x32x16_bf16 v[96:111], v[234:237], v[124:127], v[0:15]
	ds_read_b64_tr_b16 v[190:191], v172 offset:0
	ds_read_b64_tr_b16 v[192:193], v172 offset:256
	v_add_f32_e32 v189, v183, v188
	v_add_f32_e32 v189, v185, v189
	v_add_f32_e32 v189, v187, v189
	v_add_f32_e32 v189, v184, v189
	v_exp_f32_e32 v64, v64
	s_waitcnt lgkmcnt(4)
	v_mfma_f32_32x32x16_bf16 v[96:111], v[238:241], v[120:123], v[96:111]
	ds_read_b64_tr_b16 v[194:195], v172 offset:2048
	ds_read_b64_tr_b16 v[196:197], v172 offset:2304
	v_exp_f32_e32 v65, v65
	v_cvt_pk_bf16_f32 v48, v183, v188
	v_exp_f32_e32 v66, v66
	v_exp_f32_e32 v67, v67
	s_waitcnt lgkmcnt(5)
	v_mfma_f32_32x32x16_bf16 v[96:111], v[242:245], v[116:119], v[96:111]
	ds_read_b64_tr_b16 v[144:145], v172 offset:512
	ds_read_b64_tr_b16 v[146:147], v172 offset:768
	v_cvt_pk_bf16_f32 v49, v185, v187
	v_exp_f32_e32 v68, v68
	v_exp_f32_e32 v69, v69
	v_cvt_pk_bf16_f32 v50, v184, v186
	s_waitcnt lgkmcnt(6)
	v_mfma_f32_32x32x16_bf16 v[96:111], v[246:249], v[112:115], v[96:111]
	ds_read_b64_tr_b16 v[250:251], v172 offset:2560
	ds_read_b64_tr_b16 v[252:253], v172 offset:2816
	v_exp_f32_e32 v70, v70
	v_exp_f32_e32 v71, v71
	v_cvt_pk_bf16_f32 v51, v181, v182
	v_cvt_pk_bf16_f32 v52, v178, v180
	s_waitcnt lgkmcnt(6)
	v_mfma_f32_32x32x16_bf16 v[32:47], v[48:51], v[190:193], v[32:47]
	ds_read_b64_tr_b16 v[190:191], v172 offset:4096
	ds_read_b64_tr_b16 v[192:193], v172 offset:4352
	ds_read_b128 v[234:237], v164 offset:40960
	s_add_i32 m0, s26, 0xe000
	s_nop 0
	global_load_lds_dwordx4 v140, s[50:51]
	s_add_u32 s50, s50, 0x4000
	s_addc_u32 s51, s51, 0
	v_cvt_pk_bf16_f32 v53, v176, v179
	v_cvt_pk_bf16_f32 v54, v175, v177
	v_cvt_pk_bf16_f32 v55, v173, v174
	v_cvt_pk_bf16_f32 v56, v64, v65
	v_cvt_pk_bf16_f32 v57, v66, v67
	v_exp_f32_e32 v72, v72
	s_waitcnt lgkmcnt(7)
	v_mfma_f32_32x32x16_bf16 v[32:47], v[52:55], v[194:197], v[32:47]
	ds_read_b64_tr_b16 v[194:195], v172 offset:6144
	ds_read_b64_tr_b16 v[196:197], v172 offset:6400
	ds_read_b128 v[238:241], v166 offset:40960
	v_cvt_pk_bf16_f32 v58, v68, v69
	v_cvt_pk_bf16_f32 v59, v70, v71
	v_exp_f32_e32 v73, v73
	v_exp_f32_e32 v74, v74
	s_waitcnt lgkmcnt(8)
	v_mfma_f32_32x32x16_bf16 v[16:31], v[48:51], v[144:147], v[16:31]
	ds_read_b64_tr_b16 v[144:145], v172 offset:4608
	ds_read_b64_tr_b16 v[146:147], v172 offset:4864
	ds_read_b128 v[242:245], v168 offset:40960
	v_exp_f32_e32 v75, v75
	v_exp_f32_e32 v76, v76
	v_exp_f32_e32 v77, v77
	v_add_f32_e32 v189, v186, v189
	s_waitcnt lgkmcnt(9)
	v_mfma_f32_32x32x16_bf16 v[16:31], v[52:55], v[250:253], v[16:31]
	ds_read_b64_tr_b16 v[250:251], v172 offset:6656
	ds_read_b64_tr_b16 v[252:253], v172 offset:6912
	ds_read_b128 v[246:249], v170 offset:40960
	v_exp_f32_e32 v78, v78
	v_exp_f32_e32 v79, v79
	v_add_f32_e32 v189, v181, v189
	v_add_f32_e32 v189, v182, v189
	v_cvt_pk_bf16_f32 v60, v72, v73
	s_waitcnt lgkmcnt(10)
	v_mfma_f32_32x32x16_bf16 v[32:47], v[56:59], v[190:193], v[32:47]
	s_add_i32 m0, s26, 0x6000
	s_nop 0
	global_load_lds_dwordx4 v142, s[52:53]
	s_add_u32 s52, s52, 0x4000
	s_addc_u32 s53, s53, 0
	v_cvt_pk_bf16_f32 v61, v74, v75
	v_cvt_pk_bf16_f32 v62, v76, v77
	v_cvt_pk_bf16_f32 v63, v78, v79
	v_add_f32_e32 v189, v178, v189
	v_add_f32_e32 v189, v180, v189
	v_add_f32_e32 v189, v176, v189
	v_add_f32_e32 v189, v179, v189
	s_waitcnt lgkmcnt(7)
	v_mfma_f32_32x32x16_bf16 v[32:47], v[60:63], v[194:197], v[32:47]
	v_exp_f32_e32 v96, v96
	v_exp_f32_e32 v97, v97
	v_add_f32_e32 v189, v175, v189
	v_add_f32_e32 v189, v177, v189
	v_add_f32_e32 v189, v173, v189
	s_waitcnt lgkmcnt(4)
	v_mfma_f32_32x32x16_bf16 v[16:31], v[56:59], v[144:147], v[16:31]
	v_exp_f32_e32 v98, v98
	v_exp_f32_e32 v99, v99
	v_add_f32_e32 v189, v174, v189
	v_add_f32_e32 v189, v64, v189
	v_add_f32_e32 v189, v65, v189
	s_waitcnt lgkmcnt(1)
	v_mfma_f32_32x32x16_bf16 v[16:31], v[60:63], v[250:253], v[16:31]
	v_exp_f32_e32 v100, v100
	v_exp_f32_e32 v101, v101
	v_add_f32_e32 v189, v66, v189
	v_add_f32_e32 v189, v67, v189
	v_add_f32_e32 v189, v68, v189
	s_waitcnt vmcnt(2) lgkmcnt(0)
	s_barrier
	v_mfma_f32_32x32x16_bf16 v[80:95], v[234:237], v[124:127], v[0:15]
	ds_read_b128 v[234:237], v163 offset:49152
	v_exp_f32_e32 v102, v102
	v_exp_f32_e32 v103, v103
	v_add_f32_e32 v189, v69, v189
	v_add_f32_e32 v189, v70, v189
	v_add_f32_e32 v189, v71, v189
	v_mfma_f32_32x32x16_bf16 v[80:95], v[238:241], v[120:123], v[80:95]
	ds_read_b128 v[238:241], v165 offset:49152
	v_exp_f32_e32 v104, v104
	v_exp_f32_e32 v105, v105
	v_exp_f32_e32 v106, v106
	v_add_f32_e32 v189, v72, v189
	v_add_f32_e32 v189, v73, v189
	v_mfma_f32_32x32x16_bf16 v[80:95], v[242:245], v[116:119], v[80:95]
	ds_read_b128 v[242:245], v167 offset:49152
	v_exp_f32_e32 v107, v107
	v_exp_f32_e32 v108, v108
	v_exp_f32_e32 v109, v109
	v_add_f32_e32 v189, v74, v189
	v_add_f32_e32 v189, v75, v189
	v_mfma_f32_32x32x16_bf16 v[80:95], v[246:249], v[112:115], v[80:95]
	ds_read_b128 v[246:249], v169 offset:49152
	v_exp_f32_e32 v110, v110
	v_exp_f32_e32 v111, v111
	v_add_f32_e32 v189, v76, v189
	v_add_f32_e32 v189, v77, v189
	v_add_f32_e32 v189, v78, v189
	v_add_f32_e32 v189, v79, v189
	v_add_f32_e32 v160, v160, v189
	s_waitcnt lgkmcnt(3)
	v_mfma_f32_32x32x16_bf16 v[218:233], v[234:237], v[124:127], v[0:15]
	ds_read_b64_tr_b16 v[190:191], v172 offset:8192
	ds_read_b64_tr_b16 v[192:193], v172 offset:8448
	v_add_f32_e32 v189, v96, v97
	v_add_f32_e32 v189, v98, v189
	v_add_f32_e32 v189, v99, v189
	v_add_f32_e32 v189, v100, v189
	v_exp_f32_e32 v80, v80
	s_waitcnt lgkmcnt(4)
; #define LAS __attribute__((address_space(3)))
; __device__ __forceinline__ void qkt(f32x16& p0, f32x16& p1, const char* Ks, const bf16x8* qr, const f32x16& negm, int r32, int hi) {
; #pragma unroll
;     for (int d0 = 0; d0 < 4; ++d0) { const int cb = (d0 * 16 + hi * 8) * 2;
;         const bf16x8 b0 = *reinterpret_cast<const bf16x8*>(Ks + KSWZ(r32, cb));
;         const bf16x8 b1 = *reinterpret_cast<const bf16x8*>(Ks + KSWZ(r32, 128 + cb));
;         if (d0 == 0) { p0 = __builtin_amdgcn_mfma_f32_32x32x16_bf16(b0, qr[0], negm, 0, 0, 0); p1 = __builtin_amdgcn_mfma_f32_32x32x16_bf16(b1, qr[0], negm, 0, 0, 0); }
;         else { p0 = __builtin_amdgcn_mfma_f32_32x32x16_bf16(b0, qr[d0], p0, 0, 0, 0); p1 = __builtin_amdgcn_mfma_f32_32x32x16_bf16(b1, qr[d0], p1, 0, 0, 0); } }
; }
; __device__ __forceinline__ int v_st(int k, int c) { const int kk = (k & ~0xC) | ((k & 4) << 1) | ((k & 8) >> 1); return ((kk >> 3) * 2 + (c >> 5)) * 512 + ((kk & 7) * 32 + (c & 31)) * 2; }
; __device__ __forceinline__ int v_rd_base(int lane) { return (((lane & 3) << 3) | (((lane >> 2) & 3) << 6) | (((lane >> 4) & 1) << 5)) + ((lane >> 5) & 1) * 1024; }
; template <int OFF> __device__ __forceinline__ s16x4 tr_read(int vb) {
;     return __builtin_bit_cast(s16x4, __builtin_amdgcn_ds_read_tr16_b64_v4i16((LAS v4i16_t*)(unsigned)(vb + OFF)));
; }
; template <int D0> __device__ __forceinline__ void pv_one(f32x16& od, int vb, bf16x8 pa0, bf16x8 pa1, bf16x8 pa2, bf16x8 pa3) {
;     const s16x4 l0 = tr_read<v_rd_off(D0, 0, 0)>(vb), h0 = tr_read<v_rd_off(D0, 0, 1)>(vb), l1 = tr_read<v_rd_off(D0, 1, 0)>(vb), h1 = tr_read<v_rd_off(D0, 1, 1)>(vb);
;     const s16x4 l2 = tr_read<v_rd_off(D0, 2, 0)>(vb), h2 = tr_read<v_rd_off(D0, 2, 1)>(vb), l3 = tr_read<v_rd_off(D0, 3, 0)>(vb), h3 = tr_read<v_rd_off(D0, 3, 1)>(vb);
;     ...
;     od = __builtin_amdgcn_mfma_f32_32x32x16_bf16(pa0, PK(l0, h0), od, 0, 0, 0);
;     od = __builtin_amdgcn_mfma_f32_32x32x16_bf16(pa1, PK(l1, h1), od, 0, 0, 0);
;     od = __builtin_amdgcn_mfma_f32_32x32x16_bf16(pa2, PK(l2, h2), od, 0, 0, 0);
;     od = __builtin_amdgcn_mfma_f32_32x32x16_bf16(pa3, PK(l3, h3), od, 0, 0, 0);
;     ...
; }
; __device__ __forceinline__ void pv_d0(f32x16* o, int vb, bf16x8 pa0, bf16x8 pa1, bf16x8 pa2, bf16x8 pa3) {
;     pv_one<0>(o[0], vb, pa0, pa1, pa2, pa3); pv_one<1>(o[1], vb, pa0, pa1, pa2, pa3);
; }
	v_mfma_f32_32x32x16_bf16 v[218:233], v[238:241], v[120:123], v[218:233]
	ds_read_b64_tr_b16 v[194:195], v172 offset:10240
	ds_read_b64_tr_b16 v[196:197], v172 offset:10496
	v_exp_f32_e32 v81, v81
	v_cvt_pk_bf16_f32 v48, v96, v97
	v_exp_f32_e32 v82, v82
	v_exp_f32_e32 v83, v83
	s_waitcnt lgkmcnt(5)
	v_mfma_f32_32x32x16_bf16 v[218:233], v[242:245], v[116:119], v[218:233]
	ds_read_b64_tr_b16 v[144:145], v172 offset:8704
	ds_read_b64_tr_b16 v[146:147], v172 offset:8960
	v_cvt_pk_bf16_f32 v49, v98, v99
	v_exp_f32_e32 v84, v84
	v_exp_f32_e32 v85, v85
	v_cvt_pk_bf16_f32 v50, v100, v101
	s_waitcnt lgkmcnt(6)
	v_mfma_f32_32x32x16_bf16 v[218:233], v[246:249], v[112:115], v[218:233]
	ds_read_b64_tr_b16 v[250:251], v172 offset:10752
	ds_read_b64_tr_b16 v[252:253], v172 offset:11008
	v_exp_f32_e32 v86, v86
	v_exp_f32_e32 v87, v87
	v_cvt_pk_bf16_f32 v51, v102, v103
	v_cvt_pk_bf16_f32 v52, v104, v105
	s_waitcnt lgkmcnt(6)
	v_mfma_f32_32x32x16_bf16 v[32:47], v[48:51], v[190:193], v[32:47]
	ds_read_b64_tr_b16 v[190:191], v172 offset:12288
	ds_read_b64_tr_b16 v[192:193], v172 offset:12544
	ds_read_b128 v[234:237], v164 offset:49152
	s_add_i32 m0, s26, 0x8000
	s_nop 0
	global_load_lds_dwordx4 v140, s[50:51]
	s_add_u32 s50, s50, 0x4000
	s_addc_u32 s51, s51, 0
	v_cvt_pk_bf16_f32 v53, v106, v107
	v_cvt_pk_bf16_f32 v54, v108, v109
	v_cvt_pk_bf16_f32 v55, v110, v111
	v_cvt_pk_bf16_f32 v56, v80, v81
	v_cvt_pk_bf16_f32 v57, v82, v83
	v_exp_f32_e32 v88, v88
	s_waitcnt lgkmcnt(7)
	v_mfma_f32_32x32x16_bf16 v[32:47], v[52:55], v[194:197], v[32:47]
	ds_read_b64_tr_b16 v[194:195], v172 offset:14336
	ds_read_b64_tr_b16 v[196:197], v172 offset:14592
	ds_read_b128 v[238:241], v166 offset:49152
	v_cvt_pk_bf16_f32 v58, v84, v85
	v_cvt_pk_bf16_f32 v59, v86, v87
	v_exp_f32_e32 v89, v89
	v_exp_f32_e32 v90, v90
	s_waitcnt lgkmcnt(8)
	v_mfma_f32_32x32x16_bf16 v[16:31], v[48:51], v[144:147], v[16:31]
	ds_read_b64_tr_b16 v[144:145], v172 offset:12800
	ds_read_b64_tr_b16 v[146:147], v172 offset:13056
	ds_read_b128 v[242:245], v168 offset:49152
	v_exp_f32_e32 v91, v91
	v_exp_f32_e32 v92, v92
	v_exp_f32_e32 v93, v93
	v_add_f32_e32 v189, v101, v189
	s_waitcnt lgkmcnt(9)
	v_mfma_f32_32x32x16_bf16 v[16:31], v[52:55], v[250:253], v[16:31]
	ds_read_b64_tr_b16 v[250:251], v172 offset:14848
	ds_read_b64_tr_b16 v[252:253], v172 offset:15104
	ds_read_b128 v[246:249], v170 offset:49152
	v_exp_f32_e32 v94, v94
	v_exp_f32_e32 v95, v95
	v_add_f32_e32 v189, v102, v189
	v_add_f32_e32 v189, v103, v189
	v_cvt_pk_bf16_f32 v60, v88, v89
	s_waitcnt lgkmcnt(10)
	v_mfma_f32_32x32x16_bf16 v[32:47], v[56:59], v[190:193], v[32:47]
	s_mov_b32 m0, s26
	s_nop 0
	global_load_lds_dwordx4 v142, s[52:53]
	s_add_u32 s52, s52, 0x4000
	s_addc_u32 s53, s53, 0
	v_cvt_pk_bf16_f32 v61, v90, v91
	v_cvt_pk_bf16_f32 v62, v92, v93
	v_cvt_pk_bf16_f32 v63, v94, v95
	v_add_f32_e32 v189, v104, v189
	v_add_f32_e32 v189, v105, v189
	v_add_f32_e32 v189, v106, v189
	v_add_f32_e32 v189, v107, v189
	s_waitcnt lgkmcnt(7)
	v_mfma_f32_32x32x16_bf16 v[32:47], v[60:63], v[194:197], v[32:47]
	v_exp_f32_e32 v183, v218
	v_exp_f32_e32 v188, v219
	v_add_f32_e32 v189, v108, v189
	v_add_f32_e32 v189, v109, v189
	v_add_f32_e32 v189, v110, v189
	s_waitcnt lgkmcnt(4)
	v_mfma_f32_32x32x16_bf16 v[16:31], v[56:59], v[144:147], v[16:31]
	v_exp_f32_e32 v185, v220
	v_exp_f32_e32 v187, v221
	v_add_f32_e32 v189, v111, v189
	v_add_f32_e32 v189, v80, v189
	v_add_f32_e32 v189, v81, v189
	s_waitcnt lgkmcnt(1)
	v_mfma_f32_32x32x16_bf16 v[16:31], v[60:63], v[250:253], v[16:31]
	v_exp_f32_e32 v184, v222
	v_exp_f32_e32 v186, v223
	v_add_f32_e32 v189, v82, v189
	v_add_f32_e32 v189, v83, v189
	v_add_f32_e32 v189, v84, v189
	s_waitcnt vmcnt(2) lgkmcnt(0)
	s_barrier
	v_mfma_f32_32x32x16_bf16 v[64:79], v[234:237], v[124:127], v[0:15]
	ds_read_b128 v[234:237], v163 offset:57344
	v_exp_f32_e32 v181, v224
	v_exp_f32_e32 v182, v225
	v_add_f32_e32 v189, v85, v189
	v_add_f32_e32 v189, v86, v189
	v_add_f32_e32 v189, v87, v189
	v_mfma_f32_32x32x16_bf16 v[64:79], v[238:241], v[120:123], v[64:79]
	ds_read_b128 v[238:241], v165 offset:57344
	v_exp_f32_e32 v178, v226
	v_exp_f32_e32 v180, v227
	v_exp_f32_e32 v176, v228
	v_add_f32_e32 v189, v88, v189
	v_add_f32_e32 v189, v89, v189
	v_mfma_f32_32x32x16_bf16 v[64:79], v[242:245], v[116:119], v[64:79]
	ds_read_b128 v[242:245], v167 offset:57344
	v_exp_f32_e32 v179, v229
	v_exp_f32_e32 v175, v230
	v_exp_f32_e32 v177, v231
	v_add_f32_e32 v189, v90, v189
	v_add_f32_e32 v189, v91, v189
	v_mfma_f32_32x32x16_bf16 v[64:79], v[246:249], v[112:115], v[64:79]
	ds_read_b128 v[246:249], v169 offset:57344
	v_exp_f32_e32 v173, v232
	v_exp_f32_e32 v174, v233
	v_add_f32_e32 v189, v92, v189
	v_add_f32_e32 v189, v93, v189
	v_add_f32_e32 v189, v94, v189
	v_add_f32_e32 v189, v95, v189
	v_add_f32_e32 v160, v160, v189
	s_waitcnt lgkmcnt(3)
	v_mfma_f32_32x32x16_bf16 v[96:111], v[234:237], v[124:127], v[0:15]
	ds_read_b64_tr_b16 v[190:191], v172 offset:16384
	ds_read_b64_tr_b16 v[192:193], v172 offset:16640
	v_add_f32_e32 v189, v183, v188
	v_add_f32_e32 v189, v185, v189
	v_add_f32_e32 v189, v187, v189
	v_add_f32_e32 v189, v184, v189
	v_exp_f32_e32 v64, v64
	s_waitcnt lgkmcnt(4)
	v_mfma_f32_32x32x16_bf16 v[96:111], v[238:241], v[120:123], v[96:111]
	ds_read_b64_tr_b16 v[194:195], v172 offset:18432
	ds_read_b64_tr_b16 v[196:197], v172 offset:18688
	v_exp_f32_e32 v65, v65
	v_cvt_pk_bf16_f32 v48, v183, v188
	v_exp_f32_e32 v66, v66
	v_exp_f32_e32 v67, v67
	s_waitcnt lgkmcnt(5)
	v_mfma_f32_32x32x16_bf16 v[96:111], v[242:245], v[116:119], v[96:111]
	ds_read_b64_tr_b16 v[144:145], v172 offset:16896
	ds_read_b64_tr_b16 v[146:147], v172 offset:17152
	v_cvt_pk_bf16_f32 v49, v185, v187
	v_exp_f32_e32 v68, v68
	v_exp_f32_e32 v69, v69
	v_cvt_pk_bf16_f32 v50, v184, v186
	s_waitcnt lgkmcnt(6)
; #define LAS __attribute__((address_space(3)))
; __device__ __forceinline__ void qkt(f32x16& p0, f32x16& p1, const char* Ks, const bf16x8* qr, const f32x16& negm, int r32, int hi) {
; #pragma unroll
;     for (int d0 = 0; d0 < 4; ++d0) { const int cb = (d0 * 16 + hi * 8) * 2;
;         const bf16x8 b0 = *reinterpret_cast<const bf16x8*>(Ks + KSWZ(r32, cb));
;         const bf16x8 b1 = *reinterpret_cast<const bf16x8*>(Ks + KSWZ(r32, 128 + cb));
;         if (d0 == 0) { p0 = __builtin_amdgcn_mfma_f32_32x32x16_bf16(b0, qr[0], negm, 0, 0, 0); p1 = __builtin_amdgcn_mfma_f32_32x32x16_bf16(b1, qr[0], negm, 0, 0, 0); }
;         else { p0 = __builtin_amdgcn_mfma_f32_32x32x16_bf16(b0, qr[d0], p0, 0, 0, 0); p1 = __builtin_amdgcn_mfma_f32_32x32x16_bf16(b1, qr[d0], p1, 0, 0, 0); } }
; }
; __device__ __forceinline__ int v_st(int k, int c) { const int kk = (k & ~0xC) | ((k & 4) << 1) | ((k & 8) >> 1); return ((kk >> 3) * 2 + (c >> 5)) * 512 + ((kk & 7) * 32 + (c & 31)) * 2; }
; __device__ __forceinline__ int v_rd_base(int lane) { return (((lane & 3) << 3) | (((lane >> 2) & 3) << 6) | (((lane >> 4) & 1) << 5)) + ((lane >> 5) & 1) * 1024; }
; template <int OFF> __device__ __forceinline__ s16x4 tr_read(int vb) {
;     return __builtin_bit_cast(s16x4, __builtin_amdgcn_ds_read_tr16_b64_v4i16((LAS v4i16_t*)(unsigned)(vb + OFF)));
; }
; template <int D0> __device__ __forceinline__ void pv_one(f32x16& od, int vb, bf16x8 pa0, bf16x8 pa1, bf16x8 pa2, bf16x8 pa3) {
;     const s16x4 l0 = tr_read<v_rd_off(D0, 0, 0)>(vb), h0 = tr_read<v_rd_off(D0, 0, 1)>(vb), l1 = tr_read<v_rd_off(D0, 1, 0)>(vb), h1 = tr_read<v_rd_off(D0, 1, 1)>(vb);
;     const s16x4 l2 = tr_read<v_rd_off(D0, 2, 0)>(vb), h2 = tr_read<v_rd_off(D0, 2, 1)>(vb), l3 = tr_read<v_rd_off(D0, 3, 0)>(vb), h3 = tr_read<v_rd_off(D0, 3, 1)>(vb);
;     ...
;     od = __builtin_amdgcn_mfma_f32_32x32x16_bf16(pa0, PK(l0, h0), od, 0, 0, 0);
;     od = __builtin_amdgcn_mfma_f32_32x32x16_bf16(pa1, PK(l1, h1), od, 0, 0, 0);
;     od = __builtin_amdgcn_mfma_f32_32x32x16_bf16(pa2, PK(l2, h2), od, 0, 0, 0);
;     od = __builtin_amdgcn_mfma_f32_32x32x16_bf16(pa3, PK(l3, h3), od, 0, 0, 0);
;     ...
; }
; __device__ __forceinline__ void pv_d0(f32x16* o, int vb, bf16x8 pa0, bf16x8 pa1, bf16x8 pa2, bf16x8 pa3) {
;     pv_one<0>(o[0], vb, pa0, pa1, pa2, pa3); pv_one<1>(o[1], vb, pa0, pa1, pa2, pa3);
; }
	v_mfma_f32_32x32x16_bf16 v[96:111], v[246:249], v[112:115], v[96:111]
	ds_read_b64_tr_b16 v[250:251], v172 offset:18944
	ds_read_b64_tr_b16 v[252:253], v172 offset:19200
	v_exp_f32_e32 v70, v70
	v_exp_f32_e32 v71, v71
	v_cvt_pk_bf16_f32 v51, v181, v182
	v_cvt_pk_bf16_f32 v52, v178, v180
	s_waitcnt lgkmcnt(6)
	v_mfma_f32_32x32x16_bf16 v[32:47], v[48:51], v[190:193], v[32:47]
	ds_read_b64_tr_b16 v[190:191], v172 offset:20480
	ds_read_b64_tr_b16 v[192:193], v172 offset:20736
	ds_read_b128 v[234:237], v164 offset:57344
	s_add_i32 m0, s26, 0xa000
	s_nop 0
	global_load_lds_dwordx4 v140, s[50:51]
	s_add_u32 s50, s50, 0x4000
	s_addc_u32 s51, s51, 0
	v_cvt_pk_bf16_f32 v53, v176, v179
	v_cvt_pk_bf16_f32 v54, v175, v177
	v_cvt_pk_bf16_f32 v55, v173, v174
	v_cvt_pk_bf16_f32 v56, v64, v65
	v_cvt_pk_bf16_f32 v57, v66, v67
	v_exp_f32_e32 v72, v72
	s_waitcnt lgkmcnt(7)
	v_mfma_f32_32x32x16_bf16 v[32:47], v[52:55], v[194:197], v[32:47]
	ds_read_b64_tr_b16 v[194:195], v172 offset:22528
	ds_read_b64_tr_b16 v[196:197], v172 offset:22784
	ds_read_b128 v[238:241], v166 offset:57344
	v_cvt_pk_bf16_f32 v58, v68, v69
	v_cvt_pk_bf16_f32 v59, v70, v71
	v_exp_f32_e32 v73, v73
	v_exp_f32_e32 v74, v74
	s_waitcnt lgkmcnt(8)
	v_mfma_f32_32x32x16_bf16 v[16:31], v[48:51], v[144:147], v[16:31]
	ds_read_b64_tr_b16 v[144:145], v172 offset:20992
	ds_read_b64_tr_b16 v[146:147], v172 offset:21248
	ds_read_b128 v[242:245], v168 offset:57344
	v_exp_f32_e32 v75, v75
	v_exp_f32_e32 v76, v76
	v_exp_f32_e32 v77, v77
	v_add_f32_e32 v189, v186, v189
	s_waitcnt lgkmcnt(9)
	v_mfma_f32_32x32x16_bf16 v[16:31], v[52:55], v[250:253], v[16:31]
	ds_read_b64_tr_b16 v[250:251], v172 offset:23040
	ds_read_b64_tr_b16 v[252:253], v172 offset:23296
	ds_read_b128 v[246:249], v170 offset:57344
	v_exp_f32_e32 v78, v78
	v_exp_f32_e32 v79, v79
	v_add_f32_e32 v189, v181, v189
	v_add_f32_e32 v189, v182, v189
	v_cvt_pk_bf16_f32 v60, v72, v73
	s_waitcnt lgkmcnt(10)
	v_mfma_f32_32x32x16_bf16 v[32:47], v[56:59], v[190:193], v[32:47]
	s_add_i32 m0, s26, 0x2000
	s_nop 0
	global_load_lds_dwordx4 v142, s[52:53]
	s_add_u32 s52, s52, 0x4000
	s_addc_u32 s53, s53, 0
	v_cvt_pk_bf16_f32 v61, v74, v75
	v_cvt_pk_bf16_f32 v62, v76, v77
	v_cvt_pk_bf16_f32 v63, v78, v79
	v_add_f32_e32 v189, v178, v189
	v_add_f32_e32 v189, v180, v189
	v_add_f32_e32 v189, v176, v189
	v_add_f32_e32 v189, v179, v189
	s_waitcnt lgkmcnt(7)
	v_mfma_f32_32x32x16_bf16 v[32:47], v[60:63], v[194:197], v[32:47]
	v_exp_f32_e32 v96, v96
	v_exp_f32_e32 v97, v97
	v_add_f32_e32 v189, v175, v189
	v_add_f32_e32 v189, v177, v189
	v_add_f32_e32 v189, v173, v189
	s_waitcnt lgkmcnt(4)
	v_mfma_f32_32x32x16_bf16 v[16:31], v[56:59], v[144:147], v[16:31]
	v_exp_f32_e32 v98, v98
	v_exp_f32_e32 v99, v99
	v_add_f32_e32 v189, v174, v189
	v_add_f32_e32 v189, v64, v189
	v_add_f32_e32 v189, v65, v189
	s_waitcnt lgkmcnt(1)
	v_mfma_f32_32x32x16_bf16 v[16:31], v[60:63], v[250:253], v[16:31]
	v_exp_f32_e32 v100, v100
	v_exp_f32_e32 v101, v101
	v_add_f32_e32 v189, v66, v189
	v_add_f32_e32 v189, v67, v189
	v_add_f32_e32 v189, v68, v189
	s_waitcnt vmcnt(2) lgkmcnt(0)
	s_barrier
	v_mfma_f32_32x32x16_bf16 v[80:95], v[234:237], v[124:127], v[0:15]
	ds_read_b128 v[234:237], v163 offset:32768
	v_exp_f32_e32 v102, v102
	v_exp_f32_e32 v103, v103
	v_add_f32_e32 v189, v69, v189
	v_add_f32_e32 v189, v70, v189
	v_add_f32_e32 v189, v71, v189
	v_mfma_f32_32x32x16_bf16 v[80:95], v[238:241], v[120:123], v[80:95]
	ds_read_b128 v[238:241], v165 offset:32768
	v_exp_f32_e32 v104, v104
	v_exp_f32_e32 v105, v105
	v_exp_f32_e32 v106, v106
	v_add_f32_e32 v189, v72, v189
	v_add_f32_e32 v189, v73, v189
	v_mfma_f32_32x32x16_bf16 v[80:95], v[242:245], v[116:119], v[80:95]
	ds_read_b128 v[242:245], v167 offset:32768
	v_exp_f32_e32 v107, v107
	v_exp_f32_e32 v108, v108
	v_exp_f32_e32 v109, v109
	v_add_f32_e32 v189, v74, v189
	v_add_f32_e32 v189, v75, v189
	v_mfma_f32_32x32x16_bf16 v[80:95], v[246:249], v[112:115], v[80:95]
	ds_read_b128 v[246:249], v169 offset:32768
	v_exp_f32_e32 v110, v110
	v_exp_f32_e32 v111, v111
	v_add_f32_e32 v189, v76, v189
	v_add_f32_e32 v189, v77, v189
	v_add_f32_e32 v189, v78, v189
	v_add_f32_e32 v189, v79, v189
	v_add_f32_e32 v160, v160, v189
	s_waitcnt lgkmcnt(3)
	v_mfma_f32_32x32x16_bf16 v[218:233], v[234:237], v[124:127], v[0:15]
	ds_read_b64_tr_b16 v[190:191], v172 offset:24576
	ds_read_b64_tr_b16 v[192:193], v172 offset:24832
	v_add_f32_e32 v189, v96, v97
	v_add_f32_e32 v189, v98, v189
	v_add_f32_e32 v189, v99, v189
	v_add_f32_e32 v189, v100, v189
	v_exp_f32_e32 v80, v80
	s_waitcnt lgkmcnt(4)
	v_mfma_f32_32x32x16_bf16 v[218:233], v[238:241], v[120:123], v[218:233]
	ds_read_b64_tr_b16 v[194:195], v172 offset:26624
	ds_read_b64_tr_b16 v[196:197], v172 offset:26880
	v_exp_f32_e32 v81, v81
	v_cvt_pk_bf16_f32 v48, v96, v97
	v_exp_f32_e32 v82, v82
	v_exp_f32_e32 v83, v83
	s_waitcnt lgkmcnt(5)
	v_mfma_f32_32x32x16_bf16 v[218:233], v[242:245], v[116:119], v[218:233]
	ds_read_b64_tr_b16 v[144:145], v172 offset:25088
	ds_read_b64_tr_b16 v[146:147], v172 offset:25344
	v_cvt_pk_bf16_f32 v49, v98, v99
	v_exp_f32_e32 v84, v84
	v_exp_f32_e32 v85, v85
	v_cvt_pk_bf16_f32 v50, v100, v101
	s_waitcnt lgkmcnt(6)
	v_mfma_f32_32x32x16_bf16 v[218:233], v[246:249], v[112:115], v[218:233]
	ds_read_b64_tr_b16 v[250:251], v172 offset:27136
	ds_read_b64_tr_b16 v[252:253], v172 offset:27392
	v_exp_f32_e32 v86, v86
	v_exp_f32_e32 v87, v87
	v_cvt_pk_bf16_f32 v51, v102, v103
	v_cvt_pk_bf16_f32 v52, v104, v105
	s_waitcnt lgkmcnt(6)
; #define LAS __attribute__((address_space(3)))
; __device__ __forceinline__ void qkt(f32x16& p0, f32x16& p1, const char* Ks, const bf16x8* qr, const f32x16& negm, int r32, int hi) {
; #pragma unroll
;     for (int d0 = 0; d0 < 4; ++d0) { const int cb = (d0 * 16 + hi * 8) * 2;
;         const bf16x8 b0 = *reinterpret_cast<const bf16x8*>(Ks + KSWZ(r32, cb));
;         const bf16x8 b1 = *reinterpret_cast<const bf16x8*>(Ks + KSWZ(r32, 128 + cb));
;         if (d0 == 0) { p0 = __builtin_amdgcn_mfma_f32_32x32x16_bf16(b0, qr[0], negm, 0, 0, 0); p1 = __builtin_amdgcn_mfma_f32_32x32x16_bf16(b1, qr[0], negm, 0, 0, 0); }
;         else { p0 = __builtin_amdgcn_mfma_f32_32x32x16_bf16(b0, qr[d0], p0, 0, 0, 0); p1 = __builtin_amdgcn_mfma_f32_32x32x16_bf16(b1, qr[d0], p1, 0, 0, 0); } }
; }
; __device__ __forceinline__ int v_st(int k, int c) { const int kk = (k & ~0xC) | ((k & 4) << 1) | ((k & 8) >> 1); return ((kk >> 3) * 2 + (c >> 5)) * 512 + ((kk & 7) * 32 + (c & 31)) * 2; }
; __device__ __forceinline__ int v_rd_base(int lane) { return (((lane & 3) << 3) | (((lane >> 2) & 3) << 6) | (((lane >> 4) & 1) << 5)) + ((lane >> 5) & 1) * 1024; }
; template <int OFF> __device__ __forceinline__ s16x4 tr_read(int vb) {
;     return __builtin_bit_cast(s16x4, __builtin_amdgcn_ds_read_tr16_b64_v4i16((LAS v4i16_t*)(unsigned)(vb + OFF)));
; }
; template <int D0> __device__ __forceinline__ void pv_one(f32x16& od, int vb, bf16x8 pa0, bf16x8 pa1, bf16x8 pa2, bf16x8 pa3) {
;     const s16x4 l0 = tr_read<v_rd_off(D0, 0, 0)>(vb), h0 = tr_read<v_rd_off(D0, 0, 1)>(vb), l1 = tr_read<v_rd_off(D0, 1, 0)>(vb), h1 = tr_read<v_rd_off(D0, 1, 1)>(vb);
;     const s16x4 l2 = tr_read<v_rd_off(D0, 2, 0)>(vb), h2 = tr_read<v_rd_off(D0, 2, 1)>(vb), l3 = tr_read<v_rd_off(D0, 3, 0)>(vb), h3 = tr_read<v_rd_off(D0, 3, 1)>(vb);
;     ...
;     od = __builtin_amdgcn_mfma_f32_32x32x16_bf16(pa0, PK(l0, h0), od, 0, 0, 0);
;     od = __builtin_amdgcn_mfma_f32_32x32x16_bf16(pa1, PK(l1, h1), od, 0, 0, 0);
;     od = __builtin_amdgcn_mfma_f32_32x32x16_bf16(pa2, PK(l2, h2), od, 0, 0, 0);
;     od = __builtin_amdgcn_mfma_f32_32x32x16_bf16(pa3, PK(l3, h3), od, 0, 0, 0);
;     ...
; }
; __device__ __forceinline__ void pv_d0(f32x16* o, int vb, bf16x8 pa0, bf16x8 pa1, bf16x8 pa2, bf16x8 pa3) {
;     pv_one<0>(o[0], vb, pa0, pa1, pa2, pa3); pv_one<1>(o[1], vb, pa0, pa1, pa2, pa3);
; }
	v_mfma_f32_32x32x16_bf16 v[32:47], v[48:51], v[190:193], v[32:47]
	ds_read_b64_tr_b16 v[190:191], v172 offset:28672
	ds_read_b64_tr_b16 v[192:193], v172 offset:28928
	ds_read_b128 v[234:237], v164 offset:32768
	s_add_i32 m0, s26, 0xc000
	s_nop 0
	global_load_lds_dwordx4 v140, s[50:51]
	s_add_u32 s50, s50, 0x4000
	s_addc_u32 s51, s51, 0
	v_cvt_pk_bf16_f32 v53, v106, v107
	v_cvt_pk_bf16_f32 v54, v108, v109
	v_cvt_pk_bf16_f32 v55, v110, v111
	v_cvt_pk_bf16_f32 v56, v80, v81
	v_cvt_pk_bf16_f32 v57, v82, v83
	v_exp_f32_e32 v88, v88
	s_waitcnt lgkmcnt(7)
	v_mfma_f32_32x32x16_bf16 v[32:47], v[52:55], v[194:197], v[32:47]
	ds_read_b64_tr_b16 v[194:195], v172 offset:30720
	ds_read_b64_tr_b16 v[196:197], v172 offset:30976
	ds_read_b128 v[238:241], v166 offset:32768
	v_cvt_pk_bf16_f32 v58, v84, v85
	v_cvt_pk_bf16_f32 v59, v86, v87
	v_exp_f32_e32 v89, v89
	v_exp_f32_e32 v90, v90
	s_waitcnt lgkmcnt(8)
	v_mfma_f32_32x32x16_bf16 v[16:31], v[48:51], v[144:147], v[16:31]
	ds_read_b64_tr_b16 v[144:145], v172 offset:29184
	ds_read_b64_tr_b16 v[146:147], v172 offset:29440
	ds_read_b128 v[242:245], v168 offset:32768
	v_exp_f32_e32 v91, v91
	v_exp_f32_e32 v92, v92
	v_exp_f32_e32 v93, v93
	v_add_f32_e32 v189, v101, v189
	s_waitcnt lgkmcnt(9)
	v_mfma_f32_32x32x16_bf16 v[16:31], v[52:55], v[250:253], v[16:31]
	ds_read_b64_tr_b16 v[250:251], v172 offset:31232
	ds_read_b64_tr_b16 v[252:253], v172 offset:31488
	ds_read_b128 v[246:249], v170 offset:32768
	v_exp_f32_e32 v94, v94
	v_exp_f32_e32 v95, v95
	v_add_f32_e32 v189, v102, v189
	v_add_f32_e32 v189, v103, v189
	v_cvt_pk_bf16_f32 v60, v88, v89
	s_waitcnt lgkmcnt(10)
	v_mfma_f32_32x32x16_bf16 v[32:47], v[56:59], v[190:193], v[32:47]
	s_add_i32 m0, s26, 0x4000
	s_nop 0
	global_load_lds_dwordx4 v142, s[52:53]
	s_add_u32 s52, s52, 0x4000
	s_addc_u32 s53, s53, 0
	v_cvt_pk_bf16_f32 v61, v90, v91
	v_cvt_pk_bf16_f32 v62, v92, v93
	v_cvt_pk_bf16_f32 v63, v94, v95
	v_add_f32_e32 v189, v104, v189
	v_add_f32_e32 v189, v105, v189
	v_add_f32_e32 v189, v106, v189
	v_add_f32_e32 v189, v107, v189
	s_waitcnt lgkmcnt(7)
	v_mfma_f32_32x32x16_bf16 v[32:47], v[60:63], v[194:197], v[32:47]
	v_exp_f32_e32 v183, v218
	v_exp_f32_e32 v188, v219
	v_add_f32_e32 v189, v108, v189
	v_add_f32_e32 v189, v109, v189
	v_add_f32_e32 v189, v110, v189
	s_waitcnt lgkmcnt(4)
	v_mfma_f32_32x32x16_bf16 v[16:31], v[56:59], v[144:147], v[16:31]
	v_exp_f32_e32 v185, v220
	v_exp_f32_e32 v187, v221
	v_add_f32_e32 v189, v111, v189
	v_add_f32_e32 v189, v80, v189
	v_add_f32_e32 v189, v81, v189
	s_waitcnt lgkmcnt(1)
	v_mfma_f32_32x32x16_bf16 v[16:31], v[60:63], v[250:253], v[16:31]
	v_exp_f32_e32 v184, v222
	v_exp_f32_e32 v186, v223
	v_add_f32_e32 v189, v82, v189
	v_add_f32_e32 v189, v83, v189
	v_add_f32_e32 v189, v84, v189
	s_waitcnt vmcnt(2) lgkmcnt(0)
	s_barrier
	v_mfma_f32_32x32x16_bf16 v[64:79], v[234:237], v[124:127], v[0:15]
	ds_read_b128 v[234:237], v163 offset:40960
	v_exp_f32_e32 v181, v224
	v_exp_f32_e32 v182, v225
	v_add_f32_e32 v189, v85, v189
	v_add_f32_e32 v189, v86, v189
	v_add_f32_e32 v189, v87, v189
	v_mfma_f32_32x32x16_bf16 v[64:79], v[238:241], v[120:123], v[64:79]
	ds_read_b128 v[238:241], v165 offset:40960
	v_exp_f32_e32 v178, v226
	v_exp_f32_e32 v180, v227
	v_exp_f32_e32 v176, v228
	v_add_f32_e32 v189, v88, v189
	v_add_f32_e32 v189, v89, v189
	v_mfma_f32_32x32x16_bf16 v[64:79], v[242:245], v[116:119], v[64:79]
	ds_read_b128 v[242:245], v167 offset:40960
	v_exp_f32_e32 v179, v229
	v_exp_f32_e32 v175, v230
	v_exp_f32_e32 v177, v231
	v_add_f32_e32 v189, v90, v189
	v_add_f32_e32 v189, v91, v189
	v_mfma_f32_32x32x16_bf16 v[64:79], v[246:249], v[112:115], v[64:79]
	ds_read_b128 v[246:249], v169 offset:40960
	v_exp_f32_e32 v173, v232
	v_exp_f32_e32 v174, v233
	v_add_f32_e32 v189, v92, v189
	v_add_f32_e32 v189, v93, v189
	v_add_f32_e32 v189, v94, v189
	v_add_f32_e32 v189, v95, v189
	v_add_f32_e32 v160, v160, v189
	s_add_i32 s7, s7, 4
	s_cmp_lt_u32 s7, 62
	s_cbranch_scc1 .LBB0_27
	s_setprio 0
	s_waitcnt lgkmcnt(0)
	v_mov_b64_e32 v[48:49], v[0:1]
	v_mov_b64_e32 v[50:51], v[2:3]
	v_mov_b64_e32 v[52:53], v[4:5]
	v_mov_b64_e32 v[54:55], v[6:7]
	v_mov_b64_e32 v[56:57], v[8:9]
	v_mov_b64_e32 v[58:59], v[10:11]
	v_mov_b64_e32 v[60:61], v[12:13]
	v_mov_b64_e32 v[62:63], v[14:15]
	s_nop 7
	s_add_i32 s6, s6, s24
	s_cmpk_lt_i32 s6, 0x400
	s_cselect_b64 s[6:7], -1, 0
	s_or_b64 s[6:7], s[6:7], s[8:9]
	s_and_b64 s[6:7], s[86:87], s[6:7]
	s_mov_b64 s[38:39], 0x10c000
	v_lshl_add_u64 v[80:81], v[132:133], 0, s[38:39]
	s_add_i32 m0, s26, 0xe000
	v_add_u32_e32 v172, 0, v129
	global_load_lds_dwordx4 v[80:81], off
	v_lshl_add_u64 v[80:81], v[134:135], 0, s[38:39]
	s_add_i32 m0, s26, 0x6000
	s_cmp_lg_u32 0, -1
	global_load_lds_dwordx4 v[80:81], off
	ds_read_b128 v[96:99], v154 offset:40960
	ds_read_b128 v[140:143], v162 offset:40960
	s_waitcnt lgkmcnt(0)
	v_mfma_f32_32x32x16_bf16 v[80:95], v[96:99], v[124:127], v[48:63]
	s_cselect_b32 s27, 0, 0
	v_add_u32_e32 v221, s27, v129
	v_exp_f32_e32 v144, v68
	v_exp_f32_e32 v145, v69
	v_exp_f32_e32 v146, v70
	v_exp_f32_e32 v147, v71
	v_exp_f32_e32 v163, v72
	v_mfma_f32_32x32x16_bf16 v[96:111], v[140:143], v[124:127], v[48:63]
	ds_read_b128 v[140:143], v153 offset:40960
	v_exp_f32_e32 v168, v77
	v_exp_f32_e32 v169, v78
	v_exp_f32_e32 v170, v79
	s_waitcnt lgkmcnt(0)
	v_mfma_f32_32x32x16_bf16 v[80:95], v[140:143], v[120:123], v[80:95]
	ds_read_b128 v[140:143], v157 offset:40960
	s_waitcnt lgkmcnt(0)
	v_mfma_f32_32x32x16_bf16 v[96:111], v[140:143], v[120:123], v[96:111]
	ds_read_b128 v[140:143], v156 offset:40960
	s_waitcnt lgkmcnt(0)
; #define SBAR() __builtin_amdgcn_sched_barrier(0)
; #define DMA(t) do { const int t_ = (t) < NT ? (t) : NT - 1; const long off_ = (long)t_ * (KVBLK * LDK); \
;         __builtin_amdgcn_global_load_lds((const unsigned*)(kptr + off_), (LAS unsigned*)(ldsK + SLOT(t)), 16, 0, 0); \
;         __builtin_amdgcn_global_load_lds((const unsigned*)(vptr + off_), (LAS unsigned*)(ldsV + SLOT(t)), 16, 0, 0); } while (0)
; #define HALF(PX0, PX1, PY0, PY1, j_, MORE) do { \
;         SBAR(); if (MORE) DMA((j_) + 2); qkt(PX0, PX1, K_lds + SLOT(j_), qr, negm, r32, hi); \
;         finishSM(PY0, PY1, l_reg, pa0, pa1, pa2, pa3); \
;         pv_d0(o, vb0 + SLOT((j_) - 1), pa0, pa1, pa2, pa3); partialSM(PX0); \
;         if (MORE) WBAR(2); else WBAR(0); } while (0)
; __device__ __forceinline__ void attn_body(const bf16* __restrict__ Qb, const bf16* __restrict__ Kh, const bf16* __restrict__ Vh, bf16* __restrict__ Ob, int seq, float m0l2, char* lds, bool pre, bool post) {
;     ...
;     HALF(pB0, pB1, pA0, pA1, j, true);
;     HALF(pA0, pA1, pB0, pB1, j + 1, false);
;     if (post) { DMA(0); DMA(1); }
;     SBAR(); qkt(pB0, pB1, K_lds + SLOT(NT - 1), qr, negm, r32, hi);
;     finishSM(pA0, pA1, l_reg, pa0, pa1, pa2, pa3); SBAR();
;     pv_d0(o, vb0 + SLOT(NT - 2), pa0, pa1, pa2, pa3); partialSM(pB0);
	v_mfma_f32_32x32x16_bf16 v[80:95], v[140:143], v[116:119], v[80:95]
	ds_read_b128 v[140:143], v158 offset:40960
	ds_read_b128 v[164:167], v155 offset:40960
	ds_read_b128 v[190:193], v159 offset:40960
	s_waitcnt lgkmcnt(0)
	v_mfma_f32_32x32x16_bf16 v[96:111], v[140:143], v[116:119], v[96:111]
	v_exp_f32_e32 v140, v64
	v_exp_f32_e32 v141, v65
	v_exp_f32_e32 v142, v66
	v_exp_f32_e32 v143, v67
	v_cvt_pk_bf16_f32 v64, v183, v188
	v_cvt_pk_bf16_f32 v65, v185, v187
	v_cvt_pk_bf16_f32 v66, v184, v186
	v_mfma_f32_32x32x16_bf16 v[80:95], v[164:167], v[112:115], v[80:95]
	v_exp_f32_e32 v164, v73
	v_exp_f32_e32 v165, v74
	v_exp_f32_e32 v166, v75
	v_exp_f32_e32 v167, v76
	v_cvt_pk_bf16_f32 v67, v181, v182
	v_cvt_pk_bf16_f32 v68, v178, v180
	v_cvt_pk_bf16_f32 v69, v176, v179
	v_mfma_f32_32x32x16_bf16 v[96:111], v[190:193], v[112:115], v[96:111]
	v_cvt_pk_bf16_f32 v70, v175, v177
	v_cvt_pk_bf16_f32 v71, v173, v174
	v_cvt_pk_bf16_f32 v72, v140, v141
	v_cvt_pk_bf16_f32 v73, v142, v143
	v_cvt_pk_bf16_f32 v74, v144, v145
	v_cvt_pk_bf16_f32 v75, v146, v147
	v_cvt_pk_bf16_f32 v76, v163, v164
	v_cvt_pk_bf16_f32 v77, v165, v166
	v_cvt_pk_bf16_f32 v78, v167, v168
	v_cvt_pk_bf16_f32 v79, v169, v170
	ds_read_b64_tr_b16 v[190:191], v172
	ds_read_b64_tr_b16 v[192:193], v221 offset:256
	s_waitcnt lgkmcnt(0)
	v_mfma_f32_32x32x16_bf16 v[32:47], v[64:67], v[190:193], v[32:47]
	ds_read_b64_tr_b16 v[190:191], v221 offset:2048
	ds_read_b64_tr_b16 v[192:193], v221 offset:2304
	s_nop 0
	v_exp_f32_e32 v172, v80
	v_exp_f32_e32 v189, v81
	v_exp_f32_e32 v198, v90
	v_exp_f32_e32 v199, v91
	v_exp_f32_e32 v217, v92
	v_exp_f32_e32 v218, v93
	s_waitcnt lgkmcnt(0)
	v_mfma_f32_32x32x16_bf16 v[32:47], v[68:71], v[190:193], v[32:47]
	ds_read_b64_tr_b16 v[190:191], v221 offset:4096
	ds_read_b64_tr_b16 v[192:193], v221 offset:4352
	v_exp_f32_e32 v219, v94
	v_exp_f32_e32 v220, v95
	s_waitcnt lgkmcnt(0)
	v_mfma_f32_32x32x16_bf16 v[32:47], v[72:75], v[190:193], v[32:47]
	ds_read_b64_tr_b16 v[190:191], v221 offset:6144
	ds_read_b64_tr_b16 v[192:193], v221 offset:6400
	s_waitcnt lgkmcnt(0)
	v_mfma_f32_32x32x16_bf16 v[32:47], v[76:79], v[190:193], v[32:47]
	ds_read_b64_tr_b16 v[190:191], v221 offset:512
	ds_read_b64_tr_b16 v[192:193], v221 offset:768
	ds_read_b64_tr_b16 v[194:195], v221 offset:2560
	s_waitcnt lgkmcnt(0)
	v_mfma_f32_32x32x16_bf16 v[16:31], v[64:67], v[190:193], v[16:31]
	ds_read_b64_tr_b16 v[196:197], v221 offset:2816
	ds_read_b64_tr_b16 v[64:65], v221 offset:4608
	ds_read_b64_tr_b16 v[66:67], v221 offset:4864
	ds_read_b64_tr_b16 v[222:223], v221 offset:6656
	ds_read_b64_tr_b16 v[224:225], v221 offset:6912
	v_exp_f32_e32 v190, v82
	v_exp_f32_e32 v191, v83
	v_exp_f32_e32 v192, v84
	v_exp_f32_e32 v193, v85
	s_waitcnt vmcnt(2) lgkmcnt(0)
	s_barrier
; #define SBAR() __builtin_amdgcn_sched_barrier(0)
; #define DMA(t) do { const int t_ = (t) < NT ? (t) : NT - 1; const long off_ = (long)t_ * (KVBLK * LDK); \
;         __builtin_amdgcn_global_load_lds((const unsigned*)(kptr + off_), (LAS unsigned*)(ldsK + SLOT(t)), 16, 0, 0); \
;         __builtin_amdgcn_global_load_lds((const unsigned*)(vptr + off_), (LAS unsigned*)(ldsV + SLOT(t)), 16, 0, 0); } while (0)
; #define HALF(PX0, PX1, PY0, PY1, j_, MORE) do { \
;         SBAR(); if (MORE) DMA((j_) + 2); qkt(PX0, PX1, K_lds + SLOT(j_), qr, negm, r32, hi); \
;         finishSM(PY0, PY1, l_reg, pa0, pa1, pa2, pa3); \
;         pv_d0(o, vb0 + SLOT((j_) - 1), pa0, pa1, pa2, pa3); partialSM(PX0); \
;         if (MORE) WBAR(2); else WBAR(0); } while (0)
; __device__ __forceinline__ void attn_body(const bf16* __restrict__ Qb, const bf16* __restrict__ Kh, const bf16* __restrict__ Vh, bf16* __restrict__ Ob, int seq, float m0l2, char* lds, bool pre, bool post) {
;     ...
;     HALF(pA0, pA1, pB0, pB1, j + 1, false);
;     if (post) { DMA(0); DMA(1); }
;     SBAR(); qkt(pB0, pB1, K_lds + SLOT(NT - 1), qr, negm, r32, hi);
;     finishSM(pA0, pA1, l_reg, pa0, pa1, pa2, pa3); SBAR();
;     pv_d0(o, vb0 + SLOT(NT - 2), pa0, pa1, pa2, pa3); partialSM(pB0);
;     finishSM(pB0, pB1, l_reg, pa0, pa1, pa2, pa3); SBAR();
;     pv_d0(o, vb0 + SLOT(NT - 1), pa0, pa1, pa2, pa3);
	s_waitcnt lgkmcnt(0)
	v_mfma_f32_32x32x16_bf16 v[16:31], v[68:71], v[194:197], v[16:31]
	v_exp_f32_e32 v194, v86
	v_exp_f32_e32 v195, v87
	v_exp_f32_e32 v196, v88
	v_exp_f32_e32 v197, v89
	v_mfma_f32_32x32x16_bf16 v[16:31], v[72:75], v[64:67], v[16:31]
	v_mfma_f32_32x32x16_bf16 v[16:31], v[76:79], v[222:225], v[16:31]
	ds_read_b128 v[64:67], v154 offset:49152
	ds_read_b128 v[222:225], v162 offset:49152
	v_exp_f32_e32 v96, v96
	v_exp_f32_e32 v97, v97
	v_exp_f32_e32 v98, v98
	v_exp_f32_e32 v99, v99
	v_exp_f32_e32 v100, v100
	v_exp_f32_e32 v101, v101
	v_exp_f32_e32 v102, v102
	s_waitcnt lgkmcnt(0)
	v_mfma_f32_32x32x16_bf16 v[80:95], v[64:67], v[124:127], v[48:63]
	v_exp_f32_e32 v103, v103
	v_exp_f32_e32 v104, v104
	v_exp_f32_e32 v105, v105
	v_exp_f32_e32 v106, v106
	v_exp_f32_e32 v107, v107
	v_exp_f32_e32 v108, v108
	v_exp_f32_e32 v109, v109
	v_mfma_f32_32x32x16_bf16 v[64:79], v[222:225], v[124:127], v[48:63]
	ds_read_b128 v[222:225], v153 offset:49152
	v_exp_f32_e32 v110, v110
	v_exp_f32_e32 v111, v111
	s_andn2_b64 vcc, exec, s[6:7]
	s_waitcnt lgkmcnt(0)
	v_mfma_f32_32x32x16_bf16 v[80:95], v[222:225], v[120:123], v[80:95]
	ds_read_b128 v[222:225], v157 offset:49152
	s_waitcnt lgkmcnt(0)
	v_mfma_f32_32x32x16_bf16 v[64:79], v[222:225], v[120:123], v[64:79]
	ds_read_b128 v[222:225], v156 offset:49152
	s_waitcnt lgkmcnt(0)
	v_mfma_f32_32x32x16_bf16 v[80:95], v[222:225], v[116:119], v[80:95]
	ds_read_b128 v[222:225], v158 offset:49152
	s_waitcnt lgkmcnt(0)
	v_mfma_f32_32x32x16_bf16 v[64:79], v[222:225], v[116:119], v[64:79]
	ds_read_b128 v[222:225], v155 offset:49152
	s_waitcnt lgkmcnt(0)
	v_mfma_f32_32x32x16_bf16 v[80:95], v[222:225], v[112:115], v[80:95]
	ds_read_b128 v[222:225], v159 offset:49152
	s_waitcnt lgkmcnt(0)
	v_mfma_f32_32x32x16_bf16 v[64:79], v[222:225], v[112:115], v[64:79]
	v_cvt_pk_bf16_f32 v222, v172, v189
	v_cvt_pk_bf16_f32 v223, v190, v191
	v_cvt_pk_bf16_f32 v224, v192, v193
	v_cvt_pk_bf16_f32 v225, v194, v195
	v_cvt_pk_bf16_f32 v226, v196, v197
	v_cvt_pk_bf16_f32 v227, v198, v199
	v_cvt_pk_bf16_f32 v228, v217, v218
	v_cvt_pk_bf16_f32 v229, v219, v220
	v_cvt_pk_bf16_f32 v230, v96, v97
	v_cvt_pk_bf16_f32 v231, v98, v99
	v_cvt_pk_bf16_f32 v232, v100, v101
	v_cvt_pk_bf16_f32 v233, v102, v103
	v_cvt_pk_bf16_f32 v234, v104, v105
	v_cvt_pk_bf16_f32 v235, v106, v107
	v_cvt_pk_bf16_f32 v236, v108, v109
	v_cvt_pk_bf16_f32 v237, v110, v111
	ds_read_b64_tr_b16 v[238:239], v221 offset:8192
	ds_read_b64_tr_b16 v[240:241], v221 offset:8448
	s_waitcnt lgkmcnt(0)
	v_mfma_f32_32x32x16_bf16 v[32:47], v[222:225], v[238:241], v[32:47]
	ds_read_b64_tr_b16 v[238:239], v221 offset:10240
	ds_read_b64_tr_b16 v[240:241], v221 offset:10496
	s_waitcnt lgkmcnt(0)
	v_mfma_f32_32x32x16_bf16 v[32:47], v[226:229], v[238:241], v[32:47]
	ds_read_b64_tr_b16 v[238:239], v221 offset:12288
	ds_read_b64_tr_b16 v[240:241], v221 offset:12544
	s_waitcnt lgkmcnt(0)
	v_mfma_f32_32x32x16_bf16 v[32:47], v[230:233], v[238:241], v[32:47]
	ds_read_b64_tr_b16 v[238:239], v221 offset:14336
	ds_read_b64_tr_b16 v[240:241], v221 offset:14592
	s_waitcnt lgkmcnt(0)
	v_mfma_f32_32x32x16_bf16 v[32:47], v[234:237], v[238:241], v[32:47]
	ds_read_b64_tr_b16 v[238:239], v221 offset:8704
	ds_read_b64_tr_b16 v[240:241], v221 offset:8960
	s_waitcnt lgkmcnt(0)
	v_mfma_f32_32x32x16_bf16 v[16:31], v[222:225], v[238:241], v[16:31]
	ds_read_b64_tr_b16 v[222:223], v221 offset:10752
	ds_read_b64_tr_b16 v[224:225], v221 offset:11008
	s_waitcnt lgkmcnt(0)
	v_mfma_f32_32x32x16_bf16 v[16:31], v[226:229], v[222:225], v[16:31]
	ds_read_b64_tr_b16 v[222:223], v221 offset:12800
	ds_read_b64_tr_b16 v[224:225], v221 offset:13056
	s_waitcnt lgkmcnt(0)
	v_mfma_f32_32x32x16_bf16 v[16:31], v[230:233], v[222:225], v[16:31]
	ds_read_b64_tr_b16 v[222:223], v221 offset:14848
	ds_read_b64_tr_b16 v[224:225], v221 offset:15104
	s_waitcnt vmcnt(0) lgkmcnt(0)
	s_barrier
	s_waitcnt lgkmcnt(0)
	v_mfma_f32_32x32x16_bf16 v[16:31], v[234:237], v[222:225], v[16:31]
	s_cbranch_vccnz .LBB0_30
	s_add_i32 m0, s26, 0x8000
	s_add_i32 s6, s26, 0xa000
	global_load_lds_dwordx4 v[132:133], off
	s_mov_b32 m0, s26
	s_add_i32 s7, s26, 0x2000
	global_load_lds_dwordx4 v[134:135], off
	s_mov_b32 m0, s6
	s_nop 0
	global_load_lds_dwordx4 v[136:137], off
	s_mov_b32 m0, s7
	s_nop 0
	global_load_lds_dwordx4 v[138:139], off
